# v49 plus skipping the redundant clamped K/V tile reloads at the end of each differential-attention unit
# speedup vs baseline: 1.0001x; 1.0001x over previous
; #define DA_LOAD(j) do { const bf16_t* t_ = kvbase + (size_t)(j) * 64 * 4096; kreg0 = *(const u32x4*)(t_ + kgo); kreg1 = *(const u32x4*)(t_ + (kgo + 32u * 4096u)); vreg0 = *(const u32x4*)(t_ + vgo); vreg1 = *(const u32x4*)(t_ + (vgo + 4096u)); } while (0)
; __device__ __forceinline__ void da_unit(LAS unsigned char* lds, const bf16_t* __restrict__ proj, bf16_t* __restrict__ y, int unit,
;                                         const float* __restrict__ t5, float lam, float one_m_li, const float* __restrict__ subg) {
;     ...
;         DA_STORE(lds + bnn); { const int jl = j + 3 < 64 ? j + 3 : 63; DA_LOAD(jl); }
.LBB0_167:
	s_add_i32 s9, s83, 0
	s_add_i32 s8, s37, -1
	s_add_i32 s100, s9, 0x4400
	v_add_u32_e32 v64, s9, v175
	s_waitcnt lgkmcnt(0)
	s_barrier
	s_waitcnt vmcnt(3)
	ds_write_b128 v64, v[116:119]
	s_waitcnt vmcnt(2)
	ds_write_b128 v64, v[120:123] offset:8704
	v_add_u32_e32 v64, s100, v184
	s_min_u32 s8, s8, 60
	s_waitcnt vmcnt(0)
	v_perm_b32 v65, v124, v112, s66
	v_perm_b32 v66, v124, v112, s67
	s_lshl_b32 s8, s8, 19
	ds_write2_b32 v64, v65, v66 offset1:32
	v_add_u32_e32 v65, s100, v185
	s_add_u32 s8, s30, s8
	v_perm_b32 v66, v125, v113, s66
	v_perm_b32 v67, v125, v113, s67
	s_addc_u32 s9, s31, 0
	ds_write2_b32 v65, v66, v67 offset0:64 offset1:96
	v_perm_b32 v66, v126, v114, s66
	v_perm_b32 v67, v126, v114, s67
	s_add_u32 s8, s8, 0x180000
	ds_write2_b32 v64, v66, v67 offset0:128 offset1:160
	v_perm_b32 v64, v127, v115, s66
	v_perm_b32 v66, v127, v115, s67
	s_addc_u32 s9, s9, 0
	ds_write2_b32 v65, v64, v66 offset0:192 offset1:224
	s_cmp_gt_u32 s37, 61
	s_cbranch_scc1 .Lda_tail_a
	global_load_dwordx4 v[116:119], v254, s[8:9]
	global_load_dwordx4 v[124:127], v169, s[8:9]
	global_load_dwordx4 v[112:115], v173, s[8:9]
	global_load_dwordx4 v[120:123], v171, s[8:9]
.Lda_tail_a:
	s_cmp_lg_u64 s[78:79], 0
	s_cselect_b32 s100, s69, 0x19800
	s_cmp_lg_u32 s100, s6
	s_cbranch_scc0 .Lda_bcskip2
	v_mov_b32_e32 v250, 0x18c00
	ds_read_b32 v251, v250
	ds_read_b32 v250, v250 offset:1024
	s_waitcnt lgkmcnt(0)
	v_sub_f32_e32 v250, v250, v251
	v_add_f32_e32 v232, v232, v250
	v_add_f32_e32 v233, v233, v250
	v_add_f32_e32 v234, v234, v250
	v_add_f32_e32 v235, v235, v250
	v_add_f32_e32 v236, v236, v250
	v_add_f32_e32 v237, v237, v250
	v_add_f32_e32 v238, v238, v250
	v_add_f32_e32 v239, v239, v250
	v_add_f32_e32 v240, v240, v250
	v_add_f32_e32 v241, v241, v250
	v_add_f32_e32 v242, v242, v250
	v_add_f32_e32 v243, v243, v250
	v_add_f32_e32 v244, v244, v250
	v_add_f32_e32 v245, v245, v250
	v_add_f32_e32 v246, v246, v250
	v_add_f32_e32 v247, v247, v250

; #define DA_LOAD(j) do { const bf16_t* t_ = kvbase + (size_t)(j) * 64 * 4096; kreg0 = *(const u32x4*)(t_ + kgo); kreg1 = *(const u32x4*)(t_ + (kgo + 32u * 4096u)); vreg0 = *(const u32x4*)(t_ + vgo); vreg1 = *(const u32x4*)(t_ + (vgo + 4096u)); } while (0)
; __device__ __forceinline__ void da_unit(LAS unsigned char* lds, const bf16_t* __restrict__ proj, bf16_t* __restrict__ y, int unit,
;                                         const float* __restrict__ t5, float lam, float one_m_li, const float* __restrict__ subg) {
;     ...
;         DA_STORE(lds + bnn); { const int jl = j + 3 < 64 ? j + 3 : 63; DA_LOAD(jl); }
.LBB0_177:
	s_add_i32 s100, s87, 0x4400
	v_add_u32_e32 v64, s87, v175
	s_waitcnt lgkmcnt(0)
	s_barrier
	s_waitcnt vmcnt(3)
	ds_write_b128 v64, v[116:119]
	s_waitcnt vmcnt(2)
	ds_write_b128 v64, v[124:127] offset:8704
	v_add_u32_e32 v64, s100, v184
	s_min_u32 s7, s37, 60
	s_waitcnt vmcnt(0)
	v_perm_b32 v65, v120, v112, s66
	v_perm_b32 v66, v120, v112, s67
	s_lshl_b32 s7, s7, 19
	ds_write2_b32 v64, v65, v66 offset1:32
	v_add_u32_e32 v65, s100, v185
	s_add_u32 s7, s30, s7
	v_perm_b32 v66, v121, v113, s66
	v_perm_b32 v67, v121, v113, s67
	s_addc_u32 s9, s31, 0
	ds_write2_b32 v65, v66, v67 offset0:64 offset1:96
	v_perm_b32 v66, v122, v114, s66
	v_perm_b32 v67, v122, v114, s67
	s_add_u32 s8, s7, 0x180000
	ds_write2_b32 v64, v66, v67 offset0:128 offset1:160
	v_perm_b32 v64, v123, v115, s66
	v_perm_b32 v66, v123, v115, s67
	s_addc_u32 s9, s9, 0
	ds_write2_b32 v65, v64, v66 offset0:192 offset1:224
	s_cmp_gt_u32 s37, 60
	s_cbranch_scc1 .Lda_tail_b
	global_load_dwordx4 v[116:119], v254, s[8:9]
	global_load_dwordx4 v[120:123], v169, s[8:9]
	global_load_dwordx4 v[112:115], v173, s[8:9]
	global_load_dwordx4 v[124:127], v171, s[8:9]
